# P1: waves own 64 contiguous output columns (B-fragment LDS reads re-pointed); EpiProj trades bj halves between lanes fr and fr+8 so every store instruction writes 8 full 128-byte lines
# baseline (speedup 1.0000x reference)
; #define PG8_STAGE(bufoff, gbase, voff) do { _Pragma("unroll") for (int _i = 0; _i < 2; ++_i) \
;         __builtin_amdgcn_global_load_lds((const unsigned*)((const char*)(gbase) + (voff)[_i]), (LAS unsigned*)(lds + (bufoff) + ldsw + _i * 8192), 16, 0, 0); } while (0)
; #define PG8_WAIT_V(n) asm volatile("s_waitcnt vmcnt(" #n ")" ::: "memory")
; #define PG8_BAR __builtin_amdgcn_s_barrier()
; template <class Epi, bool ALIGN_EPI>
; __device__ __forceinline__ void gemm_phase(LAS unsigned char* lds, const Gemm g, const StaticOrder& S, const Epi& E) {
;     ...
;     for (int i = 0; i < 2; ++i) { int R, C; stage_rc(tid * 16 + i * 8192, R, C); const int Rb = Epi::PERM ? ((R & ~31) + perm32(R & 31)) : R;
;         voffA[i] = (unsigned)(R * lda + C) * 2u; voffB[i] = (unsigned)(Rb * K + C) * 2u; }
;     const size_t kstep = (size_t)(BK * 2);
;     const size_t hstepA = (size_t)HALF * lda * 2, hstepB = (size_t)HALF * K * 2;
;     const size_t tstepA = 2 * hstepA, tstepB = 2 * hstepB;
;     const unsigned ldsw = (unsigned)wid * 1024u;
;     const int aoff = lds_byte(wr * 64 + fr, fq * 8), boff = lds_byte(wc * 32 + fr, fq * 8);
;     ...
;     Unit cur, nxt; int ui = 0;
;     if (!S.next(0, cur)) return;
;     f32x4 acc[2][2][4][2];
; #pragma unroll
;     for (int a = 0; a < 2; ++a)
; #pragma unroll
;         for (int b = 0; b < 2; ++b)
; #pragma unroll
;             for (int m = 0; m < 4; ++m)
; #pragma unroll
;                 for (int n = 0; n < 2; ++n) acc[a][b][m][n] = (f32x4){0.f, 0.f, 0.f, 0.f};
;     bf16x8 At[4][2], B0[2][2], B1[2][2];
;     const char* cA = (const char*)g.A + (size_t)cur.pm * tstepA; const char* cB = (const char*)g.Bt + (size_t)cur.pn * tstepB;
;     PG8_STAGE(PG8_SB(0, 0), cB, voffB); PG8_STAGE(PG8_SB(0, 1), cB + hstepB, voffB); PG8_STAGE(PG8_SA(0, 0), cA, voffA); PG8_STAGE(PG8_SA(0, 1), cA + hstepA, voffA);
;     if (wr == 1) PG8_BAR;
;     PG8_WAIT_V(2); PG8_BAR;
;     PG8_STAGE(PG8_SB(1, 0), cB + kstep, voffB); PG8_STAGE(PG8_SA(1, 0), cA + kstep, voffA); PG8_STAGE(PG8_SB(1, 1), cB + hstepB + kstep, voffB);
;     PG8_WAIT_V(6); PG8_BAR;
.LBB0_326:
	s_add_u32 s12, s6, 0x6400000
	s_addc_u32 s13, s7, 0
	s_and_b32 s17, s16, 3
	s_add_i32 m0, s34, 0x18000
	v_lshl_add_u64 v[6:7], v[6:7], 0, s[66:67]
	s_lshl_b32 s38, s15, 6
	s_lshl_b32 s15, s15, 13
	s_lshl_b32 s20, s17, 5
	s_lshl_b32 s17, s17, 12
	s_waitcnt vmcnt(2)
	s_barrier
	global_load_lds_dwordx4 v[6:7], off
	v_lshl_add_u64 v[4:5], v[4:5], 0, s[66:67]
	s_add_i32 m0, s34, 0x1a000
	s_add_i32 s39, s34, 0x8000
	s_add_i32 s40, s34, 0xa000
	global_load_lds_dwordx4 v[4:5], off
	v_lshl_add_u64 v[0:1], v[0:1], 0, s[66:67]
	s_mov_b32 m0, s39
	s_add_u32 s18, s4, 0x40080
	global_load_lds_dwordx4 v[0:1], off
	v_lshl_add_u64 v[0:1], v[2:3], 0, s[66:67]
	s_mov_b32 m0, s40
	s_addc_u32 s19, s5, 0
	global_load_lds_dwordx4 v[0:1], off
	s_add_i32 m0, s34, 0x1c000
	v_lshl_add_u64 v[0:1], s[18:19], 0, v[134:135]
	global_load_lds_dwordx4 v[0:1], off
	v_lshl_add_u64 v[0:1], s[18:19], 0, v[130:131]
	s_add_i32 m0, s34, 0x1e000
	v_and_b32_e32 v148, 15, v8
	global_load_lds_dwordx4 v[0:1], off
	v_lshrrev_b32_e32 v0, 1, v8
	v_and_b32_e32 v0, 24, v0
	v_lshlrev_b32_e32 v1, 1, v0
	v_lshlrev_b32_e32 v2, 2, v8
	v_lshl_or_b32 v1, v148, 6, v1
	v_and_b32_e32 v2, 32, v2
	s_cmpk_lt_u32 s14, 0x100
	v_bitop3_b32 v3, v1, s15, v2 bitop3:0xde
	s_cselect_b64 s[14:15], -1, 0
	s_add_u32 s41, s6, 0xb400000
	v_or_b32_e32 v150, s20, v0
	s_addc_u32 s42, s7, 0
	v_bitop3_b32 v151, s20, 56, v0 bitop3:0xc8
	s_bitset1_b32 s20, 7
	v_or_b32_e32 v152, s20, v0
	v_bitop3_b32 v153, s20, 56, v0 bitop3:0xc8
	v_lshlrev_b32_e32 v0, 14, v13
	v_and_b32_e32 v0, 0xffff8000, v0
	v_bitop3_b32 v149, v1, s17, v2 bitop3:0xde
	v_add_u32_e32 v149, s17, v149
	v_lshl_add_u32 v0, v12, 11, v0
	v_and_b32_e32 v1, 1, v13
	v_lshl_or_b32 v0, v1, 6, v0
	v_lshl_add_u32 v138, v14, 1, v0
	v_lshlrev_b32_e32 v0, 14, v9
	v_and_b32_e32 v0, 0xffff8000, v0
	s_waitcnt vmcnt(6)
	v_lshl_add_u32 v0, v10, 11, v0
	v_and_b32_e32 v1, 1, v9
	v_lshl_or_b32 v0, v1, 6, v0
	v_readlane_b32 s6, v255, 10
	s_bfe_u32 s43, s16, 0x10001
	s_lshr_b32 s44, s20, 6
	v_mov_b32_e32 v139, v113
	v_lshl_add_u32 v140, v11, 1, v0
	v_mov_b32_e32 v141, v113
	s_mov_b32 s45, 0
	v_add_u32_e32 v154, 0, v3
	v_readlane_b32 s30, v255, 2
	s_mov_b32 s46, s6
	s_barrier
	v_readlane_b32 s7, v255, 11
	s_branch .LBB0_329

; #define PG8_STAGE(bufoff, gbase, voff) do { _Pragma("unroll") for (int _i = 0; _i < 2; ++_i) \
;         __builtin_amdgcn_global_load_lds((const unsigned*)((const char*)(gbase) + (voff)[_i]), (LAS unsigned*)(lds + (bufoff) + ldsw + _i * 8192), 16, 0, 0); } while (0)
; #define PG8_LDA(dst, b, h) do { _Pragma("unroll") for (int m = 0; m < 4; ++m) _Pragma("unroll") for (int k = 0; k < 2; ++k) dst[m][k] = *(const LAS bf16x8*)(lds + PG8_SA(b, h) + aoff + m * 2048 + k * 1024); } while (0)
; #define PG8_LDB(dst, b, h) do { _Pragma("unroll") for (int n = 0; n < 2; ++n) _Pragma("unroll") for (int k = 0; k < 2; ++k) dst[n][k] = *(const LAS bf16x8*)(lds + PG8_SB(b, h) + boff + n * 2048 + k * 1024); } while (0)
; #define PG8_MMA(ai, bj, At, Bt) do { __builtin_amdgcn_s_setprio(1); _Pragma("unroll") for (int m = 0; m < 4; ++m) _Pragma("unroll") for (int n = 0; n < 2; ++n) _Pragma("unroll") for (int k = 0; k < 2; ++k) \
;         acc[ai][bj][m][n] = __builtin_amdgcn_mfma_f32_16x16x32_bf16(Bt[n][k], At[m][k], acc[ai][bj][m][n], 0, 0, 0); __builtin_amdgcn_s_setprio(0); } while (0)
; #define PG8_WAIT_V(n) asm volatile("s_waitcnt vmcnt(" #n ")" ::: "memory")
; #define PG8_WAIT_L(n) asm volatile("s_waitcnt lgkmcnt(" #n ")" ::: "memory")
; #define PG8_BAR __builtin_amdgcn_s_barrier()
; #define PG8_SCHED __builtin_amdgcn_sched_barrier(0)
; template <class Epi, bool ALIGN_EPI>
; __device__ __forceinline__ void gemm_phase(LAS unsigned char* lds, const Gemm g, const StaticOrder& S, const Epi& E) {
;     ...
;         for (int t = 0; t < nt; t += 2) {
;             const bool last = (t == nt - 2);
;             const char* a1 = cA + (size_t)(t + 1) * kstep;
;             const char* a2 = last ? nA : cA + (size_t)(t + 2) * kstep; const char* b2 = last ? nB : cB + (size_t)(t + 2) * kstep;
;             const char* a3 = a2 + kstep; const char* b3 = b2 + kstep;
;             PG8_LDB(B0, 0, 0); PG8_LDB(B1, 0, 1); PG8_SCHED; PG8_LDA(At, 0, 0); PG8_STAGE(PG8_SA(1, 1), a1 + hstepA, voffA);
;             PG8_WAIT_V(8); PG8_WAIT_L(0); PG8_BAR; PG8_MMA(0, 0, At, B0); PG8_MMA(0, 1, At, B1); PG8_BAR; PG8_SCHED;
;             PG8_LDA(At, 0, 1); PG8_STAGE(PG8_SB(0, 0), b2, voffB); PG8_STAGE(PG8_SB(0, 1), b2 + hstepB, voffB); PG8_STAGE(PG8_SA(0, 0), a2, voffA);
;             PG8_WAIT_V(8); PG8_WAIT_L(0); PG8_BAR; PG8_MMA(1, 0, At, B0); PG8_MMA(1, 1, At, B1); PG8_BAR; PG8_SCHED;
.LBB0_336:
	s_add_u32 s4, s8, 0xfffc0080
	s_addc_u32 s5, s9, -1
	s_add_i32 s54, 0, 0x10000
	s_cmp_eq_u32 s51, 12
	s_cselect_b32 s27, s19, s5
	s_cselect_b32 s26, s47, s4
	v_add_u32_e32 v112, s54, v149
	s_cselect_b32 s5, s17, s50
	s_cselect_b32 s4, s48, s49
	s_add_i32 s55, 0, 0x14000
	ds_read_b128 v[142:145], v112
	ds_read_b128 v[156:159], v112 offset:1024
	ds_read_b128 v[160:163], v112 offset:2048
	ds_read_b128 v[164:167], v112 offset:3072
	v_add_u32_e32 v112, 0x11000, v149
	ds_read_b128 v[168:171], v112
	ds_read_b128 v[172:175], v112 offset:1024
	ds_read_b128 v[176:179], v112 offset:2048
	ds_read_b128 v[180:183], v112 offset:3072
	v_lshl_add_u64 v[146:147], s[8:9], 0, v[138:139]
	s_add_i32 m0, s34, 0xc000
	ds_read_b128 v[184:187], v154
	ds_read_b128 v[188:191], v154 offset:1024
	ds_read_b128 v[198:201], v154 offset:2048
	ds_read_b128 v[202:205], v154 offset:3072
	ds_read_b128 v[206:209], v154 offset:4096
	ds_read_b128 v[210:213], v154 offset:5120
	ds_read_b128 v[214:217], v154 offset:6144
	ds_read_b128 v[218:221], v154 offset:7168
	global_load_lds_dwordx4 v[146:147], off
	v_lshl_add_u64 v[146:147], s[8:9], 0, v[140:141]
	s_add_i32 m0, s34, 0xe000
	s_nop 0
	global_load_lds_dwordx4 v[146:147], off
	s_waitcnt vmcnt(8)
	s_waitcnt lgkmcnt(0)
	s_barrier
	s_setprio 1
	s_waitcnt lgkmcnt(0)
	v_mfma_f32_16x16x32_bf16 v[126:129], v[142:145], v[184:187], v[126:129]
	v_mfma_f32_16x16x32_bf16 v[122:125], v[160:163], v[184:187], v[122:125]
	v_mfma_f32_16x16x32_bf16 v[108:111], v[142:145], v[198:201], v[108:111]
	v_mfma_f32_16x16x32_bf16 v[104:107], v[160:163], v[198:201], v[104:107]
	v_mfma_f32_16x16x32_bf16 v[92:95], v[142:145], v[206:209], v[92:95]
	v_mfma_f32_16x16x32_bf16 v[88:91], v[160:163], v[206:209], v[88:91]
	v_mfma_f32_16x16x32_bf16 v[76:79], v[142:145], v[214:217], v[76:79]
	v_mfma_f32_16x16x32_bf16 v[72:75], v[160:163], v[214:217], v[72:75]
	v_mfma_f32_16x16x32_bf16 v[126:129], v[156:159], v[188:191], v[126:129]
	v_mfma_f32_16x16x32_bf16 v[122:125], v[164:167], v[188:191], v[122:125]
	v_mfma_f32_16x16x32_bf16 v[108:111], v[156:159], v[202:205], v[108:111]
	v_mfma_f32_16x16x32_bf16 v[104:107], v[164:167], v[202:205], v[104:107]
	v_mfma_f32_16x16x32_bf16 v[92:95], v[156:159], v[210:213], v[92:95]
	v_mfma_f32_16x16x32_bf16 v[88:91], v[164:167], v[210:213], v[88:91]
	v_mfma_f32_16x16x32_bf16 v[76:79], v[156:159], v[218:221], v[76:79]
	v_mfma_f32_16x16x32_bf16 v[72:75], v[164:167], v[218:221], v[72:75]
	s_setprio 0
	s_setprio 1
	v_mfma_f32_16x16x32_bf16 v[118:121], v[168:171], v[184:187], v[118:121]
	v_mfma_f32_16x16x32_bf16 v[114:117], v[176:179], v[184:187], v[114:117]
	v_mfma_f32_16x16x32_bf16 v[100:103], v[168:171], v[198:201], v[100:103]
	v_mfma_f32_16x16x32_bf16 v[96:99], v[176:179], v[198:201], v[96:99]
	v_mfma_f32_16x16x32_bf16 v[84:87], v[168:171], v[206:209], v[84:87]
	v_mfma_f32_16x16x32_bf16 v[80:83], v[176:179], v[206:209], v[80:83]
	v_mfma_f32_16x16x32_bf16 v[68:71], v[168:171], v[214:217], v[68:71]
	v_mfma_f32_16x16x32_bf16 v[64:67], v[176:179], v[214:217], v[64:67]
	v_mfma_f32_16x16x32_bf16 v[118:121], v[172:175], v[188:191], v[118:121]
	v_mfma_f32_16x16x32_bf16 v[114:117], v[180:183], v[188:191], v[114:117]
	v_mfma_f32_16x16x32_bf16 v[100:103], v[172:175], v[202:205], v[100:103]
	v_mfma_f32_16x16x32_bf16 v[96:99], v[180:183], v[202:205], v[96:99]
	v_mfma_f32_16x16x32_bf16 v[84:87], v[172:175], v[210:213], v[84:87]
	v_mfma_f32_16x16x32_bf16 v[80:83], v[180:183], v[210:213], v[80:83]
	v_mfma_f32_16x16x32_bf16 v[68:71], v[172:175], v[218:221], v[68:71]
	v_mfma_f32_16x16x32_bf16 v[64:67], v[180:183], v[218:221], v[64:67]
	s_setprio 0
	s_barrier
	s_add_i32 s54, s54, s29
	v_lshl_add_u64 v[146:147], s[4:5], 0, v[134:135]
	s_mov_b32 m0, s54
	ds_read_b128 v[184:187], v154 offset:16384
	ds_read_b128 v[188:191], v154 offset:17408
	ds_read_b128 v[198:201], v154 offset:18432
	ds_read_b128 v[202:205], v154 offset:19456
	ds_read_b128 v[206:209], v154 offset:20480
	ds_read_b128 v[210:213], v154 offset:21504
	ds_read_b128 v[214:217], v154 offset:22528
	ds_read_b128 v[218:221], v154 offset:23552
	global_load_lds_dwordx4 v[146:147], off
	s_add_i32 m0, s54, 0x2000
	s_add_u32 s56, s4, 0x40000
	v_lshl_add_u64 v[192:193], s[4:5], 0, v[130:131]
	s_addc_u32 s57, s5, 0
	s_add_i32 s54, s55, s29
	global_load_lds_dwordx4 v[192:193], off
	v_lshl_add_u64 v[222:223], s[56:57], 0, v[134:135]
	s_mov_b32 m0, s54
	v_lshl_add_u64 v[224:225], s[26:27], 0, v[132:133]
	global_load_lds_dwordx4 v[222:223], off
	v_lshl_add_u64 v[222:223], s[56:57], 0, v[130:131]
	s_add_i32 m0, s54, 0x2000
	s_nop 0
	global_load_lds_dwordx4 v[222:223], off
	v_lshl_add_u64 v[222:223], s[26:27], 0, v[136:137]
	s_mov_b32 m0, s34
	s_nop 0
	global_load_lds_dwordx4 v[222:223], off
	s_mov_b32 m0, s35
	s_nop 0
	global_load_lds_dwordx4 v[224:225], off
	s_waitcnt vmcnt(8)
	s_waitcnt lgkmcnt(0)
	s_barrier
; #define PG8_STAGE(bufoff, gbase, voff) do { _Pragma("unroll") for (int _i = 0; _i < 2; ++_i) \
;         __builtin_amdgcn_global_load_lds((const unsigned*)((const char*)(gbase) + (voff)[_i]), (LAS unsigned*)(lds + (bufoff) + ldsw + _i * 8192), 16, 0, 0); } while (0)
; #define PG8_LDA(dst, b, h) do { _Pragma("unroll") for (int m = 0; m < 4; ++m) _Pragma("unroll") for (int k = 0; k < 2; ++k) dst[m][k] = *(const LAS bf16x8*)(lds + PG8_SA(b, h) + aoff + m * 2048 + k * 1024); } while (0)
; #define PG8_LDB(dst, b, h) do { _Pragma("unroll") for (int n = 0; n < 2; ++n) _Pragma("unroll") for (int k = 0; k < 2; ++k) dst[n][k] = *(const LAS bf16x8*)(lds + PG8_SB(b, h) + boff + n * 2048 + k * 1024); } while (0)
; #define PG8_MMA(ai, bj, At, Bt) do { __builtin_amdgcn_s_setprio(1); _Pragma("unroll") for (int m = 0; m < 4; ++m) _Pragma("unroll") for (int n = 0; n < 2; ++n) _Pragma("unroll") for (int k = 0; k < 2; ++k) \
;         acc[ai][bj][m][n] = __builtin_amdgcn_mfma_f32_16x16x32_bf16(Bt[n][k], At[m][k], acc[ai][bj][m][n], 0, 0, 0); __builtin_amdgcn_s_setprio(0); } while (0)
; #define PG8_WAIT_V(n) asm volatile("s_waitcnt vmcnt(" #n ")" ::: "memory")
; #define PG8_WAIT_L(n) asm volatile("s_waitcnt lgkmcnt(" #n ")" ::: "memory")
; #define PG8_BAR __builtin_amdgcn_s_barrier()
; #define PG8_SCHED __builtin_amdgcn_sched_barrier(0)
; template <class Epi, bool ALIGN_EPI>
; __device__ __forceinline__ void gemm_phase(LAS unsigned char* lds, const Gemm g, const StaticOrder& S, const Epi& E) {
;     ...
;             PG8_WAIT_V(8); PG8_WAIT_L(0); PG8_BAR; PG8_MMA(1, 0, At, B0); PG8_MMA(1, 1, At, B1); PG8_BAR; PG8_SCHED;
;             PG8_LDB(B0, 1, 0); PG8_LDB(B1, 1, 1); PG8_SCHED; PG8_LDA(At, 1, 0); PG8_STAGE(PG8_SA(0, 1), a2 + hstepA, voffA);
;             PG8_WAIT_V(8); PG8_WAIT_L(0); PG8_BAR; PG8_MMA(0, 0, At, B0); PG8_MMA(0, 1, At, B1); PG8_BAR; PG8_SCHED;
;             PG8_LDA(At, 1, 1); PG8_STAGE(PG8_SB(1, 0), b3, voffB); PG8_STAGE(PG8_SB(1, 1), b3 + hstepB, voffB); PG8_STAGE(PG8_SA(1, 0), a3, voffA);
;             PG8_WAIT_V(8); PG8_WAIT_L(0); PG8_BAR; PG8_MMA(1, 0, At, B0); PG8_MMA(1, 1, At, B1); PG8_BAR; PG8_SCHED;
	s_setprio 1
	s_waitcnt lgkmcnt(0)
	v_mfma_f32_16x16x32_bf16 v[60:63], v[142:145], v[184:187], v[60:63]
	v_mfma_f32_16x16x32_bf16 v[56:59], v[160:163], v[184:187], v[56:59]
	v_mfma_f32_16x16x32_bf16 v[44:47], v[142:145], v[198:201], v[44:47]
	v_mfma_f32_16x16x32_bf16 v[40:43], v[160:163], v[198:201], v[40:43]
	v_mfma_f32_16x16x32_bf16 v[28:31], v[142:145], v[206:209], v[28:31]
	v_mfma_f32_16x16x32_bf16 v[24:27], v[160:163], v[206:209], v[24:27]
	v_mfma_f32_16x16x32_bf16 v[12:15], v[142:145], v[214:217], v[12:15]
	v_mfma_f32_16x16x32_bf16 v[8:11], v[160:163], v[214:217], v[8:11]
	v_mfma_f32_16x16x32_bf16 v[60:63], v[156:159], v[188:191], v[60:63]
	v_mfma_f32_16x16x32_bf16 v[56:59], v[164:167], v[188:191], v[56:59]
	v_mfma_f32_16x16x32_bf16 v[44:47], v[156:159], v[202:205], v[44:47]
	v_mfma_f32_16x16x32_bf16 v[40:43], v[164:167], v[202:205], v[40:43]
	v_mfma_f32_16x16x32_bf16 v[28:31], v[156:159], v[210:213], v[28:31]
	v_mfma_f32_16x16x32_bf16 v[24:27], v[164:167], v[210:213], v[24:27]
	v_mfma_f32_16x16x32_bf16 v[12:15], v[156:159], v[218:221], v[12:15]
	v_mfma_f32_16x16x32_bf16 v[8:11], v[164:167], v[218:221], v[8:11]
	s_setprio 0
	s_setprio 1
	v_mfma_f32_16x16x32_bf16 v[52:55], v[168:171], v[184:187], v[52:55]
	v_mfma_f32_16x16x32_bf16 v[48:51], v[176:179], v[184:187], v[48:51]
	v_mfma_f32_16x16x32_bf16 v[36:39], v[168:171], v[198:201], v[36:39]
	v_mfma_f32_16x16x32_bf16 v[32:35], v[176:179], v[198:201], v[32:35]
	v_mfma_f32_16x16x32_bf16 v[20:23], v[168:171], v[206:209], v[20:23]
	v_mfma_f32_16x16x32_bf16 v[16:19], v[176:179], v[206:209], v[16:19]
	v_mfma_f32_16x16x32_bf16 v[4:7], v[168:171], v[214:217], v[4:7]
	v_mfma_f32_16x16x32_bf16 v[0:3], v[176:179], v[214:217], v[0:3]
	v_mfma_f32_16x16x32_bf16 v[52:55], v[172:175], v[188:191], v[52:55]
	v_mfma_f32_16x16x32_bf16 v[48:51], v[180:183], v[188:191], v[48:51]
	v_mfma_f32_16x16x32_bf16 v[36:39], v[172:175], v[202:205], v[36:39]
	v_mfma_f32_16x16x32_bf16 v[32:35], v[180:183], v[202:205], v[32:35]
	v_mfma_f32_16x16x32_bf16 v[20:23], v[172:175], v[210:213], v[20:23]
	v_mfma_f32_16x16x32_bf16 v[16:19], v[180:183], v[210:213], v[16:19]
	v_mfma_f32_16x16x32_bf16 v[4:7], v[172:175], v[218:221], v[4:7]
	v_mfma_f32_16x16x32_bf16 v[0:3], v[180:183], v[218:221], v[0:3]
	s_setprio 0
	s_barrier
	s_add_i32 s54, 0, 0x18000
	v_add_u32_e32 v112, s54, v149
	s_add_i32 s55, 0, 0x1c000
	ds_read_b128 v[142:145], v112
	ds_read_b128 v[156:159], v112 offset:1024
	ds_read_b128 v[160:163], v112 offset:2048
	ds_read_b128 v[164:167], v112 offset:3072
	v_add_u32_e32 v112, 0x19000, v149
	ds_read_b128 v[168:171], v112
	ds_read_b128 v[172:175], v112 offset:1024
	ds_read_b128 v[176:179], v112 offset:2048
	ds_read_b128 v[180:183], v112 offset:3072
	s_add_u32 s26, s26, 0x40000
	s_addc_u32 s27, s27, 0
	s_mov_b32 m0, s36
	v_lshl_add_u64 v[226:227], s[26:27], 0, v[136:137]
	ds_read_b128 v[184:187], v154 offset:32768
	ds_read_b128 v[188:191], v154 offset:33792
	ds_read_b128 v[198:201], v154 offset:34816
	ds_read_b128 v[202:205], v154 offset:35840
	ds_read_b128 v[206:209], v154 offset:36864
	ds_read_b128 v[210:213], v154 offset:37888
	ds_read_b128 v[214:217], v154 offset:38912
	ds_read_b128 v[218:221], v154 offset:39936
	global_load_lds_dwordx4 v[226:227], off
	v_lshl_add_u64 v[226:227], s[26:27], 0, v[132:133]
	s_mov_b32 m0, s37
	s_nop 0
	global_load_lds_dwordx4 v[226:227], off
	s_waitcnt vmcnt(8)
	s_waitcnt lgkmcnt(0)
	s_barrier
	s_setprio 1
	s_waitcnt lgkmcnt(0)
	v_mfma_f32_16x16x32_bf16 v[126:129], v[142:145], v[184:187], v[126:129]
	v_mfma_f32_16x16x32_bf16 v[122:125], v[160:163], v[184:187], v[122:125]
	v_mfma_f32_16x16x32_bf16 v[108:111], v[142:145], v[198:201], v[108:111]
	v_mfma_f32_16x16x32_bf16 v[104:107], v[160:163], v[198:201], v[104:107]
	v_mfma_f32_16x16x32_bf16 v[92:95], v[142:145], v[206:209], v[92:95]
	v_mfma_f32_16x16x32_bf16 v[88:91], v[160:163], v[206:209], v[88:91]
	v_mfma_f32_16x16x32_bf16 v[76:79], v[142:145], v[214:217], v[76:79]
	v_mfma_f32_16x16x32_bf16 v[72:75], v[160:163], v[214:217], v[72:75]
	v_mfma_f32_16x16x32_bf16 v[126:129], v[156:159], v[188:191], v[126:129]
	v_mfma_f32_16x16x32_bf16 v[122:125], v[164:167], v[188:191], v[122:125]
	v_mfma_f32_16x16x32_bf16 v[108:111], v[156:159], v[202:205], v[108:111]
	v_mfma_f32_16x16x32_bf16 v[104:107], v[164:167], v[202:205], v[104:107]
	v_mfma_f32_16x16x32_bf16 v[92:95], v[156:159], v[210:213], v[92:95]
	v_mfma_f32_16x16x32_bf16 v[88:91], v[164:167], v[210:213], v[88:91]
	v_mfma_f32_16x16x32_bf16 v[76:79], v[156:159], v[218:221], v[76:79]
	v_mfma_f32_16x16x32_bf16 v[72:75], v[164:167], v[218:221], v[72:75]
	s_setprio 0
	s_setprio 1
	v_mfma_f32_16x16x32_bf16 v[118:121], v[168:171], v[184:187], v[118:121]
	v_mfma_f32_16x16x32_bf16 v[114:117], v[176:179], v[184:187], v[114:117]
	v_mfma_f32_16x16x32_bf16 v[100:103], v[168:171], v[198:201], v[100:103]
	v_mfma_f32_16x16x32_bf16 v[96:99], v[176:179], v[198:201], v[96:99]
	v_mfma_f32_16x16x32_bf16 v[84:87], v[168:171], v[206:209], v[84:87]
	v_mfma_f32_16x16x32_bf16 v[80:83], v[176:179], v[206:209], v[80:83]
	v_mfma_f32_16x16x32_bf16 v[68:71], v[168:171], v[214:217], v[68:71]
	v_mfma_f32_16x16x32_bf16 v[64:67], v[176:179], v[214:217], v[64:67]
	v_mfma_f32_16x16x32_bf16 v[118:121], v[172:175], v[188:191], v[118:121]
	v_mfma_f32_16x16x32_bf16 v[114:117], v[180:183], v[188:191], v[114:117]
	v_mfma_f32_16x16x32_bf16 v[100:103], v[172:175], v[202:205], v[100:103]
	v_mfma_f32_16x16x32_bf16 v[96:99], v[180:183], v[202:205], v[96:99]
	v_mfma_f32_16x16x32_bf16 v[84:87], v[172:175], v[210:213], v[84:87]
	v_mfma_f32_16x16x32_bf16 v[80:83], v[180:183], v[210:213], v[80:83]
	v_mfma_f32_16x16x32_bf16 v[68:71], v[172:175], v[218:221], v[68:71]
	v_mfma_f32_16x16x32_bf16 v[64:67], v[180:183], v[218:221], v[64:67]
	s_setprio 0
	s_barrier
; __device__ __forceinline__ unsigned pk2(float lo, float hi) { f32x2 v = {lo, hi}; bf16x2_t b = __builtin_convertvector(v, bf16x2_t); return __builtin_bit_cast(unsigned, b); }
; #define PG8_WAIT_V(n) asm volatile("s_waitcnt vmcnt(" #n ")" ::: "memory")
; #define PG8_WAIT_L(n) asm volatile("s_waitcnt lgkmcnt(" #n ")" ::: "memory")
;     __device__ __forceinline__ void operator()(const f32x4 (&acc)[2][2][4][2], const Unit& u, int wr, int wc, int fr, int fq) const {
;         const int row0 = u.pm * BM + wr * 64 + fr; const int pn = u.pn;
;         const bool rm = (pn >= 2 && pn <= 6);
;         const int hm = pn < 2 ? pn : pn - 5;
;         const int gsel = pn < 7 ? 0 : (pn - 7) / 3;
;         const int dsh = gsel == 0 ? 0 : (gsel == 1 ? 2 : 4);
; #pragma unroll
;         for (int ai = 0; ai < 2; ++ai)
; #pragma unroll
;             for (int m = 0; m < 4; ++m) {
;                 const int row = row0 + ai * HALF + m * 16;
;                 const int b = row >> 12, s = row & (SEQ - 1);
;                 const int sp = ((s & ((1 << dsh) - 1)) << (12 - dsh)) + (s >> dsh);
; #pragma unroll
;                 for (int bj = 0; bj < 2; ++bj) { const f32x4 v0 = acc[ai][bj][m][0], v1 = acc[ai][bj][m][1];
;                     u32x4 w; w.x = pk2(v0[0], v0[1]); w.y = pk2(v0[2], v0[3]); w.z = pk2(v1[0], v1[1]); w.w = pk2(v1[2], v1[3]);
;                     const int c = bj * HALF + wc * 32 + 8 * fq;
;                     bf16_t* dst = rm ? O + (size_t)row * PRM + (pn - 2) * 256 + c
;                                      : O + HM_OFF + (size_t)hm * T * 256 + ((size_t)(b * 4 + (c >> 6)) * SEQ + sp) * 64 + (c & 63);
;                     *(u32x4*)dst = w; }
; template <class Epi, bool ALIGN_EPI>
; __device__ __forceinline__ void gemm_phase(LAS unsigned char* lds, const Gemm g, const StaticOrder& S, const Epi& E) {
;     ...
;             PG8_WAIT_V(8); PG8_WAIT_L(0); PG8_BAR; PG8_MMA(0, 0, At, B0); PG8_MMA(0, 1, At, B1); PG8_BAR; PG8_SCHED;
;             PG8_LDA(At, 1, 1); PG8_STAGE(PG8_SB(1, 0), b3, voffB); PG8_STAGE(PG8_SB(1, 1), b3 + hstepB, voffB); PG8_STAGE(PG8_SA(1, 0), a3, voffA);
;             PG8_WAIT_V(8); PG8_WAIT_L(0); PG8_BAR; PG8_MMA(1, 0, At, B0); PG8_MMA(1, 1, At, B1); PG8_BAR; PG8_SCHED;
;         }
;         if constexpr (ALIGN_EPI) { if (wr == 0) PG8_BAR; }
;         if constexpr (Epi::NEEDS_LDS) E(acc, cur, wr, wc, fr, fq, lds); else E(acc, cur, wr, wc, fr, fq);
	s_add_i32 s26, s54, s29
	v_lshl_add_u64 v[146:147], v[146:147], 0, s[66:67]
	s_mov_b32 m0, s26
	ds_read_b128 v[184:187], v154 offset:49152
	ds_read_b128 v[188:191], v154 offset:50176
	ds_read_b128 v[198:201], v154 offset:51200
	ds_read_b128 v[202:205], v154 offset:52224
	ds_read_b128 v[206:209], v154 offset:53248
	ds_read_b128 v[210:213], v154 offset:54272
	ds_read_b128 v[214:217], v154 offset:55296
	ds_read_b128 v[218:221], v154 offset:56320
	global_load_lds_dwordx4 v[146:147], off
	s_add_i32 m0, s26, 0x2000
	s_add_u32 s4, s4, 0x40080
	v_lshl_add_u64 v[146:147], v[192:193], 0, s[66:67]
	s_addc_u32 s5, s5, 0
	s_add_i32 s26, s55, s29
	global_load_lds_dwordx4 v[146:147], off
	v_lshl_add_u64 v[146:147], s[4:5], 0, v[134:135]
	s_mov_b32 m0, s26
	s_nop 0
	global_load_lds_dwordx4 v[146:147], off
	v_lshl_add_u64 v[146:147], s[4:5], 0, v[130:131]
	s_add_i32 m0, s26, 0x2000
	s_nop 0
	global_load_lds_dwordx4 v[146:147], off
	v_lshl_add_u64 v[146:147], v[222:223], 0, s[66:67]
	s_mov_b32 m0, s39
	s_nop 0
	global_load_lds_dwordx4 v[146:147], off
	v_lshl_add_u64 v[146:147], v[224:225], 0, s[66:67]
	s_mov_b32 m0, s40
	s_nop 0
	global_load_lds_dwordx4 v[146:147], off
	s_waitcnt vmcnt(8)
	s_waitcnt lgkmcnt(0)
	s_barrier
	s_setprio 1
	s_waitcnt lgkmcnt(0)
	v_mfma_f32_16x16x32_bf16 v[60:63], v[142:145], v[184:187], v[60:63]
	v_mfma_f32_16x16x32_bf16 v[56:59], v[160:163], v[184:187], v[56:59]
	v_mfma_f32_16x16x32_bf16 v[44:47], v[142:145], v[198:201], v[44:47]
	v_mfma_f32_16x16x32_bf16 v[40:43], v[160:163], v[198:201], v[40:43]
	v_mfma_f32_16x16x32_bf16 v[28:31], v[142:145], v[206:209], v[28:31]
	v_mfma_f32_16x16x32_bf16 v[24:27], v[160:163], v[206:209], v[24:27]
	v_mfma_f32_16x16x32_bf16 v[12:15], v[142:145], v[214:217], v[12:15]
	v_mfma_f32_16x16x32_bf16 v[8:11], v[160:163], v[214:217], v[8:11]
	v_mfma_f32_16x16x32_bf16 v[60:63], v[156:159], v[188:191], v[60:63]
	v_mfma_f32_16x16x32_bf16 v[56:59], v[164:167], v[188:191], v[56:59]
	v_mfma_f32_16x16x32_bf16 v[44:47], v[156:159], v[202:205], v[44:47]
	v_mfma_f32_16x16x32_bf16 v[40:43], v[164:167], v[202:205], v[40:43]
	v_mfma_f32_16x16x32_bf16 v[28:31], v[156:159], v[210:213], v[28:31]
	v_mfma_f32_16x16x32_bf16 v[24:27], v[164:167], v[210:213], v[24:27]
	v_mfma_f32_16x16x32_bf16 v[12:15], v[156:159], v[218:221], v[12:15]
	v_mfma_f32_16x16x32_bf16 v[8:11], v[164:167], v[218:221], v[8:11]
	s_setprio 0
	s_setprio 1
	v_mfma_f32_16x16x32_bf16 v[52:55], v[168:171], v[184:187], v[52:55]
	v_mfma_f32_16x16x32_bf16 v[48:51], v[176:179], v[184:187], v[48:51]
	v_mfma_f32_16x16x32_bf16 v[36:39], v[168:171], v[198:201], v[36:39]
	v_mfma_f32_16x16x32_bf16 v[32:35], v[176:179], v[198:201], v[32:35]
	v_mfma_f32_16x16x32_bf16 v[20:23], v[168:171], v[206:209], v[20:23]
	v_mfma_f32_16x16x32_bf16 v[16:19], v[176:179], v[206:209], v[16:19]
	v_mfma_f32_16x16x32_bf16 v[4:7], v[168:171], v[214:217], v[4:7]
	v_mfma_f32_16x16x32_bf16 v[0:3], v[176:179], v[214:217], v[0:3]
	v_mfma_f32_16x16x32_bf16 v[52:55], v[172:175], v[188:191], v[52:55]
	v_mfma_f32_16x16x32_bf16 v[48:51], v[180:183], v[188:191], v[48:51]
	v_mfma_f32_16x16x32_bf16 v[36:39], v[172:175], v[202:205], v[36:39]
	v_mfma_f32_16x16x32_bf16 v[32:35], v[180:183], v[202:205], v[32:35]
	v_mfma_f32_16x16x32_bf16 v[20:23], v[172:175], v[210:213], v[20:23]
	v_mfma_f32_16x16x32_bf16 v[16:19], v[180:183], v[210:213], v[16:19]
	v_mfma_f32_16x16x32_bf16 v[4:7], v[172:175], v[218:221], v[4:7]
	v_mfma_f32_16x16x32_bf16 v[0:3], v[180:183], v[218:221], v[0:3]
	s_setprio 0
	s_barrier
	s_add_i32 s51, s51, 2
	s_add_u32 s8, s8, 0x100
	s_addc_u32 s9, s9, 0
	s_add_u32 s49, s49, 0x100
	s_addc_u32 s50, s50, 0
	s_cmp_gt_u32 s51, 13
	s_cbranch_scc0 .LBB0_336
	s_and_b64 vcc, exec, s[14:15]
	s_cbranch_vccz .LBB0_339
	s_barrier
.LBB0_339:
	s_lshl_b32 s4, s46, 8
	s_add_i32 s17, s4, s38
	v_readfirstlane_b32 s47, v150
	s_lshr_b32 s47, s47, 5
	v_and_b32_e32 v143, 7, v148
	v_and_b32_e32 v144, 8, v148
	v_lshlrev_b32_e32 v144, 3, v144
	v_and_b32_e32 v145, 31, v150
	v_lshl_or_b32 v144, v145, 1, v144
	v_lshlrev_b32_e32 v155, 6, v145
	s_cmp_lt_u32 s30, 2
	s_cbranch_scc1 .Lep_hm
	s_cmp_gt_u32 s30, 6
	s_cbranch_scc1 .Lep_hm
	s_add_i32 s4, s30, -2
	s_lshl_b32 s4, s4, 9
	s_lshl_b32 s5, s47, 7
	s_add_i32 s4, s4, s5
	s_add_u32 s8, s12, s4
	s_addc_u32 s9, s13, 0
	v_add_u32_e32 v142, s17, v143
	v_mul_lo_u32 v142, v142, s77
	v_add_u32_e32 v142, v142, v144
	v_cvt_pk_bf16_f32 v126, v126, v127
	v_cvt_pk_bf16_f32 v127, v128, v129
	v_cvt_pk_bf16_f32 v128, v122, v123
	v_cvt_pk_bf16_f32 v129, v124, v125
	v_cvt_pk_bf16_f32 v118, v118, v119
	v_cvt_pk_bf16_f32 v119, v120, v121
	v_cvt_pk_bf16_f32 v120, v114, v115
	v_cvt_pk_bf16_f32 v121, v116, v117
	v_mov_b32_e32 v122, v126
	v_mov_b32_e32 v123, v127
	v_mov_b32_e32 v124, v128
	v_mov_b32_e32 v125, v129
	v_mov_b32_dpp v126, v118 row_ror:8 row_mask:0xf bank_mask:0xc
	v_mov_b32_dpp v127, v119 row_ror:8 row_mask:0xf bank_mask:0xc
	v_mov_b32_dpp v128, v120 row_ror:8 row_mask:0xf bank_mask:0xc
	v_mov_b32_dpp v129, v121 row_ror:8 row_mask:0xf bank_mask:0xc
	v_mov_b32_dpp v118, v122 row_ror:8 row_mask:0xf bank_mask:0x3
	v_mov_b32_dpp v119, v123 row_ror:8 row_mask:0xf bank_mask:0x3
	v_mov_b32_dpp v120, v124 row_ror:8 row_mask:0xf bank_mask:0x3
	v_mov_b32_dpp v121, v125 row_ror:8 row_mask:0xf bank_mask:0x3
	global_store_dwordx4 v142, v[126:129], s[8:9]
	v_add_u32_e32 v142, 0x5000, v142
	global_store_dwordx4 v142, v[118:121], s[8:9]
	v_add_u32_e32 v142, 0x5000, v142
	v_cvt_pk_bf16_f32 v108, v108, v109
	v_cvt_pk_bf16_f32 v109, v110, v111
	v_cvt_pk_bf16_f32 v110, v104, v105
	v_cvt_pk_bf16_f32 v111, v106, v107
	v_cvt_pk_bf16_f32 v100, v100, v101
	v_cvt_pk_bf16_f32 v101, v102, v103
; __device__ __forceinline__ unsigned pk2(float lo, float hi) { f32x2 v = {lo, hi}; bf16x2_t b = __builtin_convertvector(v, bf16x2_t); return __builtin_bit_cast(unsigned, b); }
;     __device__ __forceinline__ void operator()(const f32x4 (&acc)[2][2][4][2], const Unit& u, int wr, int wc, int fr, int fq) const {
;     ...
; #pragma unroll
;         for (int ai = 0; ai < 2; ++ai)
; #pragma unroll
;             for (int m = 0; m < 4; ++m) {
;                 const int row = row0 + ai * HALF + m * 16;
;                 const int b = row >> 12, s = row & (SEQ - 1);
;                 const int sp = ((s & ((1 << dsh) - 1)) << (12 - dsh)) + (s >> dsh);
; #pragma unroll
;                 for (int bj = 0; bj < 2; ++bj) { const f32x4 v0 = acc[ai][bj][m][0], v1 = acc[ai][bj][m][1];
;                     u32x4 w; w.x = pk2(v0[0], v0[1]); w.y = pk2(v0[2], v0[3]); w.z = pk2(v1[0], v1[1]); w.w = pk2(v1[2], v1[3]);
;                     const int c = bj * HALF + wc * 32 + 8 * fq;
;                     bf16_t* dst = rm ? O + (size_t)row * PRM + (pn - 2) * 256 + c
;                                      : O + HM_OFF + (size_t)hm * T * 256 + ((size_t)(b * 4 + (c >> 6)) * SEQ + sp) * 64 + (c & 63);
;                     *(u32x4*)dst = w; }
	v_cvt_pk_bf16_f32 v102, v96, v97
	v_cvt_pk_bf16_f32 v103, v98, v99
	v_mov_b32_e32 v104, v108
	v_mov_b32_e32 v105, v109
	v_mov_b32_e32 v106, v110
	v_mov_b32_e32 v107, v111
	v_mov_b32_dpp v108, v100 row_ror:8 row_mask:0xf bank_mask:0xc
	v_mov_b32_dpp v109, v101 row_ror:8 row_mask:0xf bank_mask:0xc
	v_mov_b32_dpp v110, v102 row_ror:8 row_mask:0xf bank_mask:0xc
	v_mov_b32_dpp v111, v103 row_ror:8 row_mask:0xf bank_mask:0xc
	v_mov_b32_dpp v100, v104 row_ror:8 row_mask:0xf bank_mask:0x3
	v_mov_b32_dpp v101, v105 row_ror:8 row_mask:0xf bank_mask:0x3
	v_mov_b32_dpp v102, v106 row_ror:8 row_mask:0xf bank_mask:0x3
	v_mov_b32_dpp v103, v107 row_ror:8 row_mask:0xf bank_mask:0x3
	global_store_dwordx4 v142, v[108:111], s[8:9]
	v_add_u32_e32 v142, 0x5000, v142
	global_store_dwordx4 v142, v[100:103], s[8:9]
	v_add_u32_e32 v142, 0x5000, v142
	v_cvt_pk_bf16_f32 v92, v92, v93
	v_cvt_pk_bf16_f32 v93, v94, v95
	v_cvt_pk_bf16_f32 v94, v88, v89
	v_cvt_pk_bf16_f32 v95, v90, v91
	v_cvt_pk_bf16_f32 v84, v84, v85
	v_cvt_pk_bf16_f32 v85, v86, v87
	v_cvt_pk_bf16_f32 v86, v80, v81
	v_cvt_pk_bf16_f32 v87, v82, v83
	v_mov_b32_e32 v88, v92
	v_mov_b32_e32 v89, v93
	v_mov_b32_e32 v90, v94
	v_mov_b32_e32 v91, v95
	v_mov_b32_dpp v92, v84 row_ror:8 row_mask:0xf bank_mask:0xc
	v_mov_b32_dpp v93, v85 row_ror:8 row_mask:0xf bank_mask:0xc
	v_mov_b32_dpp v94, v86 row_ror:8 row_mask:0xf bank_mask:0xc
	v_mov_b32_dpp v95, v87 row_ror:8 row_mask:0xf bank_mask:0xc
	v_mov_b32_dpp v84, v88 row_ror:8 row_mask:0xf bank_mask:0x3
	v_mov_b32_dpp v85, v89 row_ror:8 row_mask:0xf bank_mask:0x3
	v_mov_b32_dpp v86, v90 row_ror:8 row_mask:0xf bank_mask:0x3
	v_mov_b32_dpp v87, v91 row_ror:8 row_mask:0xf bank_mask:0x3
	global_store_dwordx4 v142, v[92:95], s[8:9]
	v_add_u32_e32 v142, 0x5000, v142
	global_store_dwordx4 v142, v[84:87], s[8:9]
	v_add_u32_e32 v142, 0x5000, v142
	v_cvt_pk_bf16_f32 v76, v76, v77
	v_cvt_pk_bf16_f32 v77, v78, v79
	v_cvt_pk_bf16_f32 v78, v72, v73
	v_cvt_pk_bf16_f32 v79, v74, v75
	v_cvt_pk_bf16_f32 v68, v68, v69
	v_cvt_pk_bf16_f32 v69, v70, v71
	v_cvt_pk_bf16_f32 v70, v64, v65
	v_cvt_pk_bf16_f32 v71, v66, v67
	v_mov_b32_e32 v72, v76
	v_mov_b32_e32 v73, v77
	v_mov_b32_e32 v74, v78
	v_mov_b32_e32 v75, v79
	v_mov_b32_dpp v76, v68 row_ror:8 row_mask:0xf bank_mask:0xc
	v_mov_b32_dpp v77, v69 row_ror:8 row_mask:0xf bank_mask:0xc
	v_mov_b32_dpp v78, v70 row_ror:8 row_mask:0xf bank_mask:0xc
	v_mov_b32_dpp v79, v71 row_ror:8 row_mask:0xf bank_mask:0xc
	v_mov_b32_dpp v68, v72 row_ror:8 row_mask:0xf bank_mask:0x3
	v_mov_b32_dpp v69, v73 row_ror:8 row_mask:0xf bank_mask:0x3
	v_mov_b32_dpp v70, v74 row_ror:8 row_mask:0xf bank_mask:0x3
	v_mov_b32_dpp v71, v75 row_ror:8 row_mask:0xf bank_mask:0x3
	global_store_dwordx4 v142, v[76:79], s[8:9]
	v_add_u32_e32 v142, 0x5000, v142
	global_store_dwordx4 v142, v[68:71], s[8:9]
	v_add_u32_e32 v142, 0x2d000, v142
	v_cvt_pk_bf16_f32 v60, v60, v61
	v_cvt_pk_bf16_f32 v61, v62, v63
	v_cvt_pk_bf16_f32 v62, v56, v57
	v_cvt_pk_bf16_f32 v63, v58, v59
	v_cvt_pk_bf16_f32 v52, v52, v53
	v_cvt_pk_bf16_f32 v53, v54, v55
	v_cvt_pk_bf16_f32 v54, v48, v49
	v_cvt_pk_bf16_f32 v55, v50, v51
	v_mov_b32_e32 v56, v60
	v_mov_b32_e32 v57, v61
	v_mov_b32_e32 v58, v62
	v_mov_b32_e32 v59, v63
	v_mov_b32_dpp v60, v52 row_ror:8 row_mask:0xf bank_mask:0xc
	v_mov_b32_dpp v61, v53 row_ror:8 row_mask:0xf bank_mask:0xc
	v_mov_b32_dpp v62, v54 row_ror:8 row_mask:0xf bank_mask:0xc
	v_mov_b32_dpp v63, v55 row_ror:8 row_mask:0xf bank_mask:0xc
	v_mov_b32_dpp v52, v56 row_ror:8 row_mask:0xf bank_mask:0x3
	v_mov_b32_dpp v53, v57 row_ror:8 row_mask:0xf bank_mask:0x3
	v_mov_b32_dpp v54, v58 row_ror:8 row_mask:0xf bank_mask:0x3
	v_mov_b32_dpp v55, v59 row_ror:8 row_mask:0xf bank_mask:0x3
	global_store_dwordx4 v142, v[60:63], s[8:9]
	v_add_u32_e32 v142, 0x5000, v142
	global_store_dwordx4 v142, v[52:55], s[8:9]
	v_add_u32_e32 v142, 0x5000, v142
	v_cvt_pk_bf16_f32 v44, v44, v45
	v_cvt_pk_bf16_f32 v45, v46, v47
	v_cvt_pk_bf16_f32 v46, v40, v41
	v_cvt_pk_bf16_f32 v47, v42, v43
	v_cvt_pk_bf16_f32 v36, v36, v37
	v_cvt_pk_bf16_f32 v37, v38, v39
	v_cvt_pk_bf16_f32 v38, v32, v33
	v_cvt_pk_bf16_f32 v39, v34, v35
	v_mov_b32_e32 v40, v44
	v_mov_b32_e32 v41, v45
	v_mov_b32_e32 v42, v46
	v_mov_b32_e32 v43, v47
	v_mov_b32_dpp v44, v36 row_ror:8 row_mask:0xf bank_mask:0xc
	v_mov_b32_dpp v45, v37 row_ror:8 row_mask:0xf bank_mask:0xc
	v_mov_b32_dpp v46, v38 row_ror:8 row_mask:0xf bank_mask:0xc
	v_mov_b32_dpp v47, v39 row_ror:8 row_mask:0xf bank_mask:0xc
	v_mov_b32_dpp v36, v40 row_ror:8 row_mask:0xf bank_mask:0x3
	v_mov_b32_dpp v37, v41 row_ror:8 row_mask:0xf bank_mask:0x3
	v_mov_b32_dpp v38, v42 row_ror:8 row_mask:0xf bank_mask:0x3
	v_mov_b32_dpp v39, v43 row_ror:8 row_mask:0xf bank_mask:0x3
	global_store_dwordx4 v142, v[44:47], s[8:9]
	v_add_u32_e32 v142, 0x5000, v142
	global_store_dwordx4 v142, v[36:39], s[8:9]
	v_add_u32_e32 v142, 0x5000, v142
	v_cvt_pk_bf16_f32 v28, v28, v29
	v_cvt_pk_bf16_f32 v29, v30, v31
	v_cvt_pk_bf16_f32 v30, v24, v25
	v_cvt_pk_bf16_f32 v31, v26, v27
	v_cvt_pk_bf16_f32 v20, v20, v21
	v_cvt_pk_bf16_f32 v21, v22, v23
	v_cvt_pk_bf16_f32 v22, v16, v17
	v_cvt_pk_bf16_f32 v23, v18, v19
	v_mov_b32_e32 v24, v28
	v_mov_b32_e32 v25, v29
	v_mov_b32_e32 v26, v30
	v_mov_b32_e32 v27, v31
	v_mov_b32_dpp v28, v20 row_ror:8 row_mask:0xf bank_mask:0xc
	v_mov_b32_dpp v29, v21 row_ror:8 row_mask:0xf bank_mask:0xc
	v_mov_b32_dpp v30, v22 row_ror:8 row_mask:0xf bank_mask:0xc
	v_mov_b32_dpp v31, v23 row_ror:8 row_mask:0xf bank_mask:0xc
	v_mov_b32_dpp v20, v24 row_ror:8 row_mask:0xf bank_mask:0x3
	v_mov_b32_dpp v21, v25 row_ror:8 row_mask:0xf bank_mask:0x3
	v_mov_b32_dpp v22, v26 row_ror:8 row_mask:0xf bank_mask:0x3
	v_mov_b32_dpp v23, v27 row_ror:8 row_mask:0xf bank_mask:0x3
	global_store_dwordx4 v142, v[28:31], s[8:9]
	v_add_u32_e32 v142, 0x5000, v142
	global_store_dwordx4 v142, v[20:23], s[8:9]
	v_add_u32_e32 v142, 0x5000, v142
	v_cvt_pk_bf16_f32 v12, v12, v13
	v_cvt_pk_bf16_f32 v13, v14, v15
	v_cvt_pk_bf16_f32 v14, v8, v9
	v_cvt_pk_bf16_f32 v15, v10, v11
	v_cvt_pk_bf16_f32 v4, v4, v5
	v_cvt_pk_bf16_f32 v5, v6, v7
	v_cvt_pk_bf16_f32 v6, v0, v1
	v_cvt_pk_bf16_f32 v7, v2, v3
	v_mov_b32_e32 v8, v12
	v_mov_b32_e32 v9, v13
	v_mov_b32_e32 v10, v14
	v_mov_b32_e32 v11, v15
	v_mov_b32_dpp v12, v4 row_ror:8 row_mask:0xf bank_mask:0xc
	v_mov_b32_dpp v13, v5 row_ror:8 row_mask:0xf bank_mask:0xc
	v_mov_b32_dpp v14, v6 row_ror:8 row_mask:0xf bank_mask:0xc
	v_mov_b32_dpp v15, v7 row_ror:8 row_mask:0xf bank_mask:0xc
	v_mov_b32_dpp v4, v8 row_ror:8 row_mask:0xf bank_mask:0x3
	v_mov_b32_dpp v5, v9 row_ror:8 row_mask:0xf bank_mask:0x3
	v_mov_b32_dpp v6, v10 row_ror:8 row_mask:0xf bank_mask:0x3
	v_mov_b32_dpp v7, v11 row_ror:8 row_mask:0xf bank_mask:0x3
	global_store_dwordx4 v142, v[12:15], s[8:9]
	v_add_u32_e32 v142, 0x5000, v142
	global_store_dwordx4 v142, v[4:7], s[8:9]
	s_branch .Lep_done
; __device__ __forceinline__ unsigned pk2(float lo, float hi) { f32x2 v = {lo, hi}; bf16x2_t b = __builtin_convertvector(v, bf16x2_t); return __builtin_bit_cast(unsigned, b); }
;     __device__ __forceinline__ void operator()(const f32x4 (&acc)[2][2][4][2], const Unit& u, int wr, int wc, int fr, int fq) const {
;         const int row0 = u.pm * BM + wr * 64 + fr; const int pn = u.pn;
;         const bool rm = (pn >= 2 && pn <= 6);
;         const int hm = pn < 2 ? pn : pn - 5;
;         const int gsel = pn < 7 ? 0 : (pn - 7) / 3;
;         const int dsh = gsel == 0 ? 0 : (gsel == 1 ? 2 : 4);
; #pragma unroll
;         for (int ai = 0; ai < 2; ++ai)
; #pragma unroll
;             for (int m = 0; m < 4; ++m) {
;                 const int row = row0 + ai * HALF + m * 16;
;                 const int b = row >> 12, s = row & (SEQ - 1);
;                 const int sp = ((s & ((1 << dsh) - 1)) << (12 - dsh)) + (s >> dsh);
; #pragma unroll
;                 for (int bj = 0; bj < 2; ++bj) { const f32x4 v0 = acc[ai][bj][m][0], v1 = acc[ai][bj][m][1];
;                     u32x4 w; w.x = pk2(v0[0], v0[1]); w.y = pk2(v0[2], v0[3]); w.z = pk2(v1[0], v1[1]); w.w = pk2(v1[2], v1[3]);
;                     const int c = bj * HALF + wc * 32 + 8 * fq;
;                     bf16_t* dst = rm ? O + (size_t)row * PRM + (pn - 2) * 256 + c
;                                      : O + HM_OFF + (size_t)hm * T * 256 + ((size_t)(b * 4 + (c >> 6)) * SEQ + sp) * 64 + (c & 63);
;                     *(u32x4*)dst = w; }
.Lep_hm:
	s_add_i32 s8, s30, -5
	s_cmp_lt_u32 s30, 2
	s_cselect_b32 s8, s30, s8
	s_mov_b32 s19, 0
	s_mov_b32 s98, 0
	s_cmp_lg_u32 s30, 1
	s_cbranch_scc1 .Lep_hm1
	s_cmp_lt_u32 s47, 2
	s_cselect_b32 s98, 1, 0
.Lep_hm1:
	s_cmp_lt_u32 s30, 7
	s_cbranch_scc1 .Lep_hm2
	s_add_i32 s4, s30, -7
	s_mul_i32 s5, s4, 11
	s_lshr_b32 s5, s5, 5
	s_lshl_b32 s19, s5, 1
	s_mul_i32 s5, s5, 3
	s_sub_i32 s4, s4, s5
	s_cmp_eq_u32 s4, 1
	s_cselect_b32 s98, 1, 0
.Lep_hm2:
	s_lshr_b32 s4, s46, 2
	s_and_b32 s4, s4, -4
	s_or_b32 s4, s4, s47
	s_lshl_b32 s4, s4, 19
	s_lshl_b32 s8, s8, 24
	s_add_i32 s4, s4, s8
	s_add_u32 s26, s41, s4
	s_addc_u32 s27, s42, 0
	s_sub_i32 s30, 12, s19
	s_lshl_b32 s46, 1, s19
	s_add_i32 s46, s46, -1
	s_and_b32 s17, s17, 0xfff
	s_cmp_lg_u32 s98, 0
	s_cbranch_scc1 .Lep_k
	v_cvt_pk_bf16_f32 v126, v126, v127
	v_cvt_pk_bf16_f32 v127, v128, v129
	v_cvt_pk_bf16_f32 v128, v122, v123
	v_cvt_pk_bf16_f32 v129, v124, v125
	v_cvt_pk_bf16_f32 v118, v118, v119
	v_cvt_pk_bf16_f32 v119, v120, v121
	v_cvt_pk_bf16_f32 v120, v114, v115
	v_cvt_pk_bf16_f32 v121, v116, v117
	v_mov_b32_e32 v122, v126
	v_mov_b32_e32 v123, v127
	v_mov_b32_e32 v124, v128
	v_mov_b32_e32 v125, v129
	v_mov_b32_dpp v126, v118 row_ror:8 row_mask:0xf bank_mask:0xc
	v_mov_b32_dpp v127, v119 row_ror:8 row_mask:0xf bank_mask:0xc
	v_mov_b32_dpp v128, v120 row_ror:8 row_mask:0xf bank_mask:0xc
	v_mov_b32_dpp v129, v121 row_ror:8 row_mask:0xf bank_mask:0xc
	v_mov_b32_dpp v118, v122 row_ror:8 row_mask:0xf bank_mask:0x3
	v_mov_b32_dpp v119, v123 row_ror:8 row_mask:0xf bank_mask:0x3
	v_mov_b32_dpp v120, v124 row_ror:8 row_mask:0xf bank_mask:0x3
	v_mov_b32_dpp v121, v125 row_ror:8 row_mask:0xf bank_mask:0x3
	v_add_u32_e32 v145, s17, v143
	v_and_b32_e32 v146, s46, v145
	v_lshlrev_b32_e32 v146, s30, v146
	v_lshrrev_b32_e32 v145, s19, v145
	v_add_u32_e32 v145, v145, v146
	v_lshl_add_u32 v112, v145, 7, v144
	global_store_dwordx4 v112, v[126:129], s[26:27]
	s_add_i32 s47, s17, 8
	v_add_u32_e32 v145, s47, v143
	v_and_b32_e32 v146, s46, v145
	v_lshlrev_b32_e32 v146, s30, v146
	v_lshrrev_b32_e32 v145, s19, v145
	v_add_u32_e32 v145, v145, v146
	v_lshl_add_u32 v112, v145, 7, v144
	global_store_dwordx4 v112, v[118:121], s[26:27]
	v_cvt_pk_bf16_f32 v108, v108, v109
	v_cvt_pk_bf16_f32 v109, v110, v111
	v_cvt_pk_bf16_f32 v110, v104, v105
	v_cvt_pk_bf16_f32 v111, v106, v107
	v_cvt_pk_bf16_f32 v100, v100, v101
	v_cvt_pk_bf16_f32 v101, v102, v103
	v_cvt_pk_bf16_f32 v102, v96, v97
	v_cvt_pk_bf16_f32 v103, v98, v99
	v_mov_b32_e32 v104, v108
	v_mov_b32_e32 v105, v109
	v_mov_b32_e32 v106, v110
	v_mov_b32_e32 v107, v111
	v_mov_b32_dpp v108, v100 row_ror:8 row_mask:0xf bank_mask:0xc
	v_mov_b32_dpp v109, v101 row_ror:8 row_mask:0xf bank_mask:0xc
	v_mov_b32_dpp v110, v102 row_ror:8 row_mask:0xf bank_mask:0xc
	v_mov_b32_dpp v111, v103 row_ror:8 row_mask:0xf bank_mask:0xc
	v_mov_b32_dpp v100, v104 row_ror:8 row_mask:0xf bank_mask:0x3
	v_mov_b32_dpp v101, v105 row_ror:8 row_mask:0xf bank_mask:0x3
	v_mov_b32_dpp v102, v106 row_ror:8 row_mask:0xf bank_mask:0x3
	v_mov_b32_dpp v103, v107 row_ror:8 row_mask:0xf bank_mask:0x3
	s_add_i32 s47, s17, 16
	v_add_u32_e32 v145, s47, v143
	v_and_b32_e32 v146, s46, v145
	v_lshlrev_b32_e32 v146, s30, v146
	v_lshrrev_b32_e32 v145, s19, v145
	v_add_u32_e32 v145, v145, v146
	v_lshl_add_u32 v112, v145, 7, v144
	global_store_dwordx4 v112, v[108:111], s[26:27]
	s_add_i32 s47, s17, 24
	v_add_u32_e32 v145, s47, v143
	v_and_b32_e32 v146, s46, v145
	v_lshlrev_b32_e32 v146, s30, v146
	v_lshrrev_b32_e32 v145, s19, v145
	v_add_u32_e32 v145, v145, v146
	v_lshl_add_u32 v112, v145, 7, v144
	global_store_dwordx4 v112, v[100:103], s[26:27]
	v_cvt_pk_bf16_f32 v92, v92, v93
	v_cvt_pk_bf16_f32 v93, v94, v95
	v_cvt_pk_bf16_f32 v94, v88, v89
	v_cvt_pk_bf16_f32 v95, v90, v91
	v_cvt_pk_bf16_f32 v84, v84, v85
	v_cvt_pk_bf16_f32 v85, v86, v87
	v_cvt_pk_bf16_f32 v86, v80, v81
	v_cvt_pk_bf16_f32 v87, v82, v83
	v_mov_b32_e32 v88, v92
	v_mov_b32_e32 v89, v93
	v_mov_b32_e32 v90, v94
	v_mov_b32_e32 v91, v95
	v_mov_b32_dpp v92, v84 row_ror:8 row_mask:0xf bank_mask:0xc
	v_mov_b32_dpp v93, v85 row_ror:8 row_mask:0xf bank_mask:0xc
	v_mov_b32_dpp v94, v86 row_ror:8 row_mask:0xf bank_mask:0xc
	v_mov_b32_dpp v95, v87 row_ror:8 row_mask:0xf bank_mask:0xc
	v_mov_b32_dpp v84, v88 row_ror:8 row_mask:0xf bank_mask:0x3
	v_mov_b32_dpp v85, v89 row_ror:8 row_mask:0xf bank_mask:0x3
	v_mov_b32_dpp v86, v90 row_ror:8 row_mask:0xf bank_mask:0x3
	v_mov_b32_dpp v87, v91 row_ror:8 row_mask:0xf bank_mask:0x3
	s_add_i32 s47, s17, 32
	v_add_u32_e32 v145, s47, v143
	v_and_b32_e32 v146, s46, v145
	v_lshlrev_b32_e32 v146, s30, v146
	v_lshrrev_b32_e32 v145, s19, v145
	v_add_u32_e32 v145, v145, v146
	v_lshl_add_u32 v112, v145, 7, v144
	global_store_dwordx4 v112, v[92:95], s[26:27]
	s_add_i32 s47, s17, 40
	v_add_u32_e32 v145, s47, v143
	v_and_b32_e32 v146, s46, v145
	v_lshlrev_b32_e32 v146, s30, v146
	v_lshrrev_b32_e32 v145, s19, v145
	v_add_u32_e32 v145, v145, v146
	v_lshl_add_u32 v112, v145, 7, v144
	global_store_dwordx4 v112, v[84:87], s[26:27]
	v_cvt_pk_bf16_f32 v76, v76, v77
	v_cvt_pk_bf16_f32 v77, v78, v79
	v_cvt_pk_bf16_f32 v78, v72, v73
	v_cvt_pk_bf16_f32 v79, v74, v75
	v_cvt_pk_bf16_f32 v68, v68, v69
	v_cvt_pk_bf16_f32 v69, v70, v71
	v_cvt_pk_bf16_f32 v70, v64, v65
	v_cvt_pk_bf16_f32 v71, v66, v67
	v_mov_b32_e32 v72, v76
	v_mov_b32_e32 v73, v77
	v_mov_b32_e32 v74, v78
	v_mov_b32_e32 v75, v79
	v_mov_b32_dpp v76, v68 row_ror:8 row_mask:0xf bank_mask:0xc
	v_mov_b32_dpp v77, v69 row_ror:8 row_mask:0xf bank_mask:0xc
	v_mov_b32_dpp v78, v70 row_ror:8 row_mask:0xf bank_mask:0xc
	v_mov_b32_dpp v79, v71 row_ror:8 row_mask:0xf bank_mask:0xc
; __device__ __forceinline__ unsigned pk2(float lo, float hi) { f32x2 v = {lo, hi}; bf16x2_t b = __builtin_convertvector(v, bf16x2_t); return __builtin_bit_cast(unsigned, b); }
;     __device__ __forceinline__ void operator()(const f32x4 (&acc)[2][2][4][2], const Unit& u, int wr, int wc, int fr, int fq) const {
;         const int row0 = u.pm * BM + wr * 64 + fr; const int pn = u.pn;
;         const bool rm = (pn >= 2 && pn <= 6);
;         const int hm = pn < 2 ? pn : pn - 5;
;         const int gsel = pn < 7 ? 0 : (pn - 7) / 3;
;         const int dsh = gsel == 0 ? 0 : (gsel == 1 ? 2 : 4);
; #pragma unroll
;         for (int ai = 0; ai < 2; ++ai)
; #pragma unroll
;             for (int m = 0; m < 4; ++m) {
;                 const int row = row0 + ai * HALF + m * 16;
;                 const int b = row >> 12, s = row & (SEQ - 1);
;                 const int sp = ((s & ((1 << dsh) - 1)) << (12 - dsh)) + (s >> dsh);
; #pragma unroll
;                 for (int bj = 0; bj < 2; ++bj) { const f32x4 v0 = acc[ai][bj][m][0], v1 = acc[ai][bj][m][1];
;                     u32x4 w; w.x = pk2(v0[0], v0[1]); w.y = pk2(v0[2], v0[3]); w.z = pk2(v1[0], v1[1]); w.w = pk2(v1[2], v1[3]);
;                     const int c = bj * HALF + wc * 32 + 8 * fq;
;                     bf16_t* dst = rm ? O + (size_t)row * PRM + (pn - 2) * 256 + c
;                                      : O + HM_OFF + (size_t)hm * T * 256 + ((size_t)(b * 4 + (c >> 6)) * SEQ + sp) * 64 + (c & 63);
;                     *(u32x4*)dst = w; }
	v_mov_b32_dpp v68, v72 row_ror:8 row_mask:0xf bank_mask:0x3
	v_mov_b32_dpp v69, v73 row_ror:8 row_mask:0xf bank_mask:0x3
	v_mov_b32_dpp v70, v74 row_ror:8 row_mask:0xf bank_mask:0x3
	v_mov_b32_dpp v71, v75 row_ror:8 row_mask:0xf bank_mask:0x3
	s_add_i32 s47, s17, 48
	v_add_u32_e32 v145, s47, v143
	v_and_b32_e32 v146, s46, v145
	v_lshlrev_b32_e32 v146, s30, v146
	v_lshrrev_b32_e32 v145, s19, v145
	v_add_u32_e32 v145, v145, v146
	v_lshl_add_u32 v112, v145, 7, v144
	global_store_dwordx4 v112, v[76:79], s[26:27]
	s_add_i32 s47, s17, 56
	v_add_u32_e32 v145, s47, v143
	v_and_b32_e32 v146, s46, v145
	v_lshlrev_b32_e32 v146, s30, v146
	v_lshrrev_b32_e32 v145, s19, v145
	v_add_u32_e32 v145, v145, v146
	v_lshl_add_u32 v112, v145, 7, v144
	global_store_dwordx4 v112, v[68:71], s[26:27]
	v_cvt_pk_bf16_f32 v60, v60, v61
	v_cvt_pk_bf16_f32 v61, v62, v63
	v_cvt_pk_bf16_f32 v62, v56, v57
	v_cvt_pk_bf16_f32 v63, v58, v59
	v_cvt_pk_bf16_f32 v52, v52, v53
	v_cvt_pk_bf16_f32 v53, v54, v55
	v_cvt_pk_bf16_f32 v54, v48, v49
	v_cvt_pk_bf16_f32 v55, v50, v51
	v_mov_b32_e32 v56, v60
	v_mov_b32_e32 v57, v61
	v_mov_b32_e32 v58, v62
	v_mov_b32_e32 v59, v63
	v_mov_b32_dpp v60, v52 row_ror:8 row_mask:0xf bank_mask:0xc
	v_mov_b32_dpp v61, v53 row_ror:8 row_mask:0xf bank_mask:0xc
	v_mov_b32_dpp v62, v54 row_ror:8 row_mask:0xf bank_mask:0xc
	v_mov_b32_dpp v63, v55 row_ror:8 row_mask:0xf bank_mask:0xc
	v_mov_b32_dpp v52, v56 row_ror:8 row_mask:0xf bank_mask:0x3
	v_mov_b32_dpp v53, v57 row_ror:8 row_mask:0xf bank_mask:0x3
	v_mov_b32_dpp v54, v58 row_ror:8 row_mask:0xf bank_mask:0x3
	v_mov_b32_dpp v55, v59 row_ror:8 row_mask:0xf bank_mask:0x3
	s_add_i32 s47, s17, 128
	v_add_u32_e32 v145, s47, v143
	v_and_b32_e32 v146, s46, v145
	v_lshlrev_b32_e32 v146, s30, v146
	v_lshrrev_b32_e32 v145, s19, v145
	v_add_u32_e32 v145, v145, v146
	v_lshl_add_u32 v112, v145, 7, v144
	global_store_dwordx4 v112, v[60:63], s[26:27]
	s_add_i32 s47, s17, 136
	v_add_u32_e32 v145, s47, v143
	v_and_b32_e32 v146, s46, v145
	v_lshlrev_b32_e32 v146, s30, v146
	v_lshrrev_b32_e32 v145, s19, v145
	v_add_u32_e32 v145, v145, v146
	v_lshl_add_u32 v112, v145, 7, v144
	global_store_dwordx4 v112, v[52:55], s[26:27]
	v_cvt_pk_bf16_f32 v44, v44, v45
	v_cvt_pk_bf16_f32 v45, v46, v47
	v_cvt_pk_bf16_f32 v46, v40, v41
	v_cvt_pk_bf16_f32 v47, v42, v43
	v_cvt_pk_bf16_f32 v36, v36, v37
	v_cvt_pk_bf16_f32 v37, v38, v39
	v_cvt_pk_bf16_f32 v38, v32, v33
	v_cvt_pk_bf16_f32 v39, v34, v35
	v_mov_b32_e32 v40, v44
	v_mov_b32_e32 v41, v45
	v_mov_b32_e32 v42, v46
	v_mov_b32_e32 v43, v47
	v_mov_b32_dpp v44, v36 row_ror:8 row_mask:0xf bank_mask:0xc
	v_mov_b32_dpp v45, v37 row_ror:8 row_mask:0xf bank_mask:0xc
	v_mov_b32_dpp v46, v38 row_ror:8 row_mask:0xf bank_mask:0xc
	v_mov_b32_dpp v47, v39 row_ror:8 row_mask:0xf bank_mask:0xc
	v_mov_b32_dpp v36, v40 row_ror:8 row_mask:0xf bank_mask:0x3
	v_mov_b32_dpp v37, v41 row_ror:8 row_mask:0xf bank_mask:0x3
	v_mov_b32_dpp v38, v42 row_ror:8 row_mask:0xf bank_mask:0x3
	v_mov_b32_dpp v39, v43 row_ror:8 row_mask:0xf bank_mask:0x3
	s_add_i32 s47, s17, 144
	v_add_u32_e32 v145, s47, v143
	v_and_b32_e32 v146, s46, v145
	v_lshlrev_b32_e32 v146, s30, v146
	v_lshrrev_b32_e32 v145, s19, v145
	v_add_u32_e32 v145, v145, v146
	v_lshl_add_u32 v112, v145, 7, v144
	global_store_dwordx4 v112, v[44:47], s[26:27]
	s_add_i32 s47, s17, 152
	v_add_u32_e32 v145, s47, v143
	v_and_b32_e32 v146, s46, v145
	v_lshlrev_b32_e32 v146, s30, v146
	v_lshrrev_b32_e32 v145, s19, v145
	v_add_u32_e32 v145, v145, v146
	v_lshl_add_u32 v112, v145, 7, v144
	global_store_dwordx4 v112, v[36:39], s[26:27]
	v_cvt_pk_bf16_f32 v28, v28, v29
	v_cvt_pk_bf16_f32 v29, v30, v31
	v_cvt_pk_bf16_f32 v30, v24, v25
	v_cvt_pk_bf16_f32 v31, v26, v27
	v_cvt_pk_bf16_f32 v20, v20, v21
	v_cvt_pk_bf16_f32 v21, v22, v23
	v_cvt_pk_bf16_f32 v22, v16, v17
	v_cvt_pk_bf16_f32 v23, v18, v19
	v_mov_b32_e32 v24, v28
	v_mov_b32_e32 v25, v29
	v_mov_b32_e32 v26, v30
	v_mov_b32_e32 v27, v31
	v_mov_b32_dpp v28, v20 row_ror:8 row_mask:0xf bank_mask:0xc
	v_mov_b32_dpp v29, v21 row_ror:8 row_mask:0xf bank_mask:0xc
	v_mov_b32_dpp v30, v22 row_ror:8 row_mask:0xf bank_mask:0xc
	v_mov_b32_dpp v31, v23 row_ror:8 row_mask:0xf bank_mask:0xc
	v_mov_b32_dpp v20, v24 row_ror:8 row_mask:0xf bank_mask:0x3
	v_mov_b32_dpp v21, v25 row_ror:8 row_mask:0xf bank_mask:0x3
	v_mov_b32_dpp v22, v26 row_ror:8 row_mask:0xf bank_mask:0x3
	v_mov_b32_dpp v23, v27 row_ror:8 row_mask:0xf bank_mask:0x3
	s_add_i32 s47, s17, 160
	v_add_u32_e32 v145, s47, v143
	v_and_b32_e32 v146, s46, v145
	v_lshlrev_b32_e32 v146, s30, v146
	v_lshrrev_b32_e32 v145, s19, v145
	v_add_u32_e32 v145, v145, v146
	v_lshl_add_u32 v112, v145, 7, v144
	global_store_dwordx4 v112, v[28:31], s[26:27]
	s_add_i32 s47, s17, 168
	v_add_u32_e32 v145, s47, v143
	v_and_b32_e32 v146, s46, v145
	v_lshlrev_b32_e32 v146, s30, v146
	v_lshrrev_b32_e32 v145, s19, v145
	v_add_u32_e32 v145, v145, v146
	v_lshl_add_u32 v112, v145, 7, v144
	global_store_dwordx4 v112, v[20:23], s[26:27]
	v_cvt_pk_bf16_f32 v12, v12, v13
	v_cvt_pk_bf16_f32 v13, v14, v15
	v_cvt_pk_bf16_f32 v14, v8, v9
	v_cvt_pk_bf16_f32 v15, v10, v11
	v_cvt_pk_bf16_f32 v4, v4, v5
	v_cvt_pk_bf16_f32 v5, v6, v7
	v_cvt_pk_bf16_f32 v6, v0, v1
	v_cvt_pk_bf16_f32 v7, v2, v3
	v_mov_b32_e32 v8, v12
	v_mov_b32_e32 v9, v13
	v_mov_b32_e32 v10, v14
	v_mov_b32_e32 v11, v15
	v_mov_b32_dpp v12, v4 row_ror:8 row_mask:0xf bank_mask:0xc
	v_mov_b32_dpp v13, v5 row_ror:8 row_mask:0xf bank_mask:0xc
	v_mov_b32_dpp v14, v6 row_ror:8 row_mask:0xf bank_mask:0xc
	v_mov_b32_dpp v15, v7 row_ror:8 row_mask:0xf bank_mask:0xc
	v_mov_b32_dpp v4, v8 row_ror:8 row_mask:0xf bank_mask:0x3
	v_mov_b32_dpp v5, v9 row_ror:8 row_mask:0xf bank_mask:0x3
	v_mov_b32_dpp v6, v10 row_ror:8 row_mask:0xf bank_mask:0x3
	v_mov_b32_dpp v7, v11 row_ror:8 row_mask:0xf bank_mask:0x3
	s_add_i32 s47, s17, 176
	v_add_u32_e32 v145, s47, v143
	v_and_b32_e32 v146, s46, v145
	v_lshlrev_b32_e32 v146, s30, v146
	v_lshrrev_b32_e32 v145, s19, v145
	v_add_u32_e32 v145, v145, v146
	v_lshl_add_u32 v112, v145, 7, v144
	global_store_dwordx4 v112, v[12:15], s[26:27]
	s_add_i32 s47, s17, 184
	v_add_u32_e32 v145, s47, v143
	v_and_b32_e32 v146, s46, v145
	v_lshlrev_b32_e32 v146, s30, v146
	v_lshrrev_b32_e32 v145, s19, v145
	v_add_u32_e32 v145, v145, v146
	v_lshl_add_u32 v112, v145, 7, v144
	global_store_dwordx4 v112, v[4:7], s[26:27]
	s_branch .Lep_done
; __device__ __forceinline__ unsigned pk2(float lo, float hi) { f32x2 v = {lo, hi}; bf16x2_t b = __builtin_convertvector(v, bf16x2_t); return __builtin_bit_cast(unsigned, b); }
;     __device__ __forceinline__ void operator()(const f32x4 (&acc)[2][2][4][2], const Unit& u, int wr, int wc, int fr, int fq) const {
;         const int row0 = u.pm * BM + wr * 64 + fr; const int pn = u.pn;
;         const bool rm = (pn >= 2 && pn <= 6);
;         const int hm = pn < 2 ? pn : pn - 5;
;         const int gsel = pn < 7 ? 0 : (pn - 7) / 3;
;         const int dsh = gsel == 0 ? 0 : (gsel == 1 ? 2 : 4);
; #pragma unroll
;         for (int ai = 0; ai < 2; ++ai)
; #pragma unroll
;             for (int m = 0; m < 4; ++m) {
;                 const int row = row0 + ai * HALF + m * 16;
;                 const int b = row >> 12, s = row & (SEQ - 1);
;                 const int sp = ((s & ((1 << dsh) - 1)) << (12 - dsh)) + (s >> dsh);
; #pragma unroll
;                 for (int bj = 0; bj < 2; ++bj) { const f32x4 v0 = acc[ai][bj][m][0], v1 = acc[ai][bj][m][1];
;                     u32x4 w; w.x = pk2(v0[0], v0[1]); w.y = pk2(v0[2], v0[3]); w.z = pk2(v1[0], v1[1]); w.w = pk2(v1[2], v1[3]);
;                     const int c = bj * HALF + wc * 32 + 8 * fq;
;                     bf16_t* dst = rm ? O + (size_t)row * PRM + (pn - 2) * 256 + c
;                                      : O + HM_OFF + (size_t)hm * T * 256 + ((size_t)(b * 4 + (c >> 6)) * SEQ + sp) * 64 + (c & 63);
;                     *(u32x4*)dst = w; }
.Lep_k:
	v_cvt_pk_bf16_f32 v126, v126, v127
	v_cvt_pk_bf16_f32 v127, v128, v129
	v_cvt_pk_bf16_f32 v128, v122, v123
	v_cvt_pk_bf16_f32 v129, v124, v125
	v_cvt_pk_bf16_f32 v118, v118, v119
	v_cvt_pk_bf16_f32 v119, v120, v121
	v_cvt_pk_bf16_f32 v120, v114, v115
	v_cvt_pk_bf16_f32 v121, v116, v117
	v_add_u32_e32 v145, s17, v148
	v_and_b32_e32 v146, s46, v145
	v_lshlrev_b32_e32 v146, s30, v146
	v_lshrrev_b32_e32 v145, s19, v145
	v_add_u32_e32 v145, v145, v146
	v_lshrrev_b32_e32 v146, 5, v145
	v_and_b32_e32 v147, 31, v145
	v_lshlrev_b32_e32 v146, 12, v146
	v_lshl_or_b32 v146, v147, 4, v146
	v_add_u32_e32 v112, v146, v155
	global_store_dwordx4 v112, v[126:129], s[26:27]
	global_store_dwordx4 v112, v[118:121], s[26:27] offset:2048
	v_cvt_pk_bf16_f32 v108, v108, v109
	v_cvt_pk_bf16_f32 v109, v110, v111
	v_cvt_pk_bf16_f32 v110, v104, v105
	v_cvt_pk_bf16_f32 v111, v106, v107
	v_cvt_pk_bf16_f32 v100, v100, v101
	v_cvt_pk_bf16_f32 v101, v102, v103
	v_cvt_pk_bf16_f32 v102, v96, v97
	v_cvt_pk_bf16_f32 v103, v98, v99
	s_add_i32 s47, s17, 16
	v_add_u32_e32 v145, s47, v148
	v_and_b32_e32 v146, s46, v145
	v_lshlrev_b32_e32 v146, s30, v146
	v_lshrrev_b32_e32 v145, s19, v145
	v_add_u32_e32 v145, v145, v146
	v_lshrrev_b32_e32 v146, 5, v145
	v_and_b32_e32 v147, 31, v145
	v_lshlrev_b32_e32 v146, 12, v146
	v_lshl_or_b32 v146, v147, 4, v146
	v_add_u32_e32 v112, v146, v155
	global_store_dwordx4 v112, v[108:111], s[26:27]
	global_store_dwordx4 v112, v[100:103], s[26:27] offset:2048
	v_cvt_pk_bf16_f32 v92, v92, v93
	v_cvt_pk_bf16_f32 v93, v94, v95
	v_cvt_pk_bf16_f32 v94, v88, v89
	v_cvt_pk_bf16_f32 v95, v90, v91
	v_cvt_pk_bf16_f32 v84, v84, v85
	v_cvt_pk_bf16_f32 v85, v86, v87
	v_cvt_pk_bf16_f32 v86, v80, v81
	v_cvt_pk_bf16_f32 v87, v82, v83
	s_add_i32 s47, s17, 32
	v_add_u32_e32 v145, s47, v148
	v_and_b32_e32 v146, s46, v145
	v_lshlrev_b32_e32 v146, s30, v146
	v_lshrrev_b32_e32 v145, s19, v145
	v_add_u32_e32 v145, v145, v146
	v_lshrrev_b32_e32 v146, 5, v145
	v_and_b32_e32 v147, 31, v145
	v_lshlrev_b32_e32 v146, 12, v146
	v_lshl_or_b32 v146, v147, 4, v146
	v_add_u32_e32 v112, v146, v155
	global_store_dwordx4 v112, v[92:95], s[26:27]
	global_store_dwordx4 v112, v[84:87], s[26:27] offset:2048
	v_cvt_pk_bf16_f32 v76, v76, v77
	v_cvt_pk_bf16_f32 v77, v78, v79
	v_cvt_pk_bf16_f32 v78, v72, v73
	v_cvt_pk_bf16_f32 v79, v74, v75
	v_cvt_pk_bf16_f32 v68, v68, v69
	v_cvt_pk_bf16_f32 v69, v70, v71
	v_cvt_pk_bf16_f32 v70, v64, v65
	v_cvt_pk_bf16_f32 v71, v66, v67
	s_add_i32 s47, s17, 48
	v_add_u32_e32 v145, s47, v148
	v_and_b32_e32 v146, s46, v145
	v_lshlrev_b32_e32 v146, s30, v146
	v_lshrrev_b32_e32 v145, s19, v145
	v_add_u32_e32 v145, v145, v146
	v_lshrrev_b32_e32 v146, 5, v145
	v_and_b32_e32 v147, 31, v145
	v_lshlrev_b32_e32 v146, 12, v146
	v_lshl_or_b32 v146, v147, 4, v146
	v_add_u32_e32 v112, v146, v155
	global_store_dwordx4 v112, v[76:79], s[26:27]
	global_store_dwordx4 v112, v[68:71], s[26:27] offset:2048
	v_cvt_pk_bf16_f32 v60, v60, v61
	v_cvt_pk_bf16_f32 v61, v62, v63
	v_cvt_pk_bf16_f32 v62, v56, v57
	v_cvt_pk_bf16_f32 v63, v58, v59
	v_cvt_pk_bf16_f32 v52, v52, v53
	v_cvt_pk_bf16_f32 v53, v54, v55
	v_cvt_pk_bf16_f32 v54, v48, v49
	v_cvt_pk_bf16_f32 v55, v50, v51
	s_add_i32 s47, s17, 128
	v_add_u32_e32 v145, s47, v148
	v_and_b32_e32 v146, s46, v145
	v_lshlrev_b32_e32 v146, s30, v146
	v_lshrrev_b32_e32 v145, s19, v145
	v_add_u32_e32 v145, v145, v146
	v_lshrrev_b32_e32 v146, 5, v145
	v_and_b32_e32 v147, 31, v145
	v_lshlrev_b32_e32 v146, 12, v146
	v_lshl_or_b32 v146, v147, 4, v146
	v_add_u32_e32 v112, v146, v155
	global_store_dwordx4 v112, v[60:63], s[26:27]
	global_store_dwordx4 v112, v[52:55], s[26:27] offset:2048
	v_cvt_pk_bf16_f32 v44, v44, v45
	v_cvt_pk_bf16_f32 v45, v46, v47
	v_cvt_pk_bf16_f32 v46, v40, v41
	v_cvt_pk_bf16_f32 v47, v42, v43
	v_cvt_pk_bf16_f32 v36, v36, v37
	v_cvt_pk_bf16_f32 v37, v38, v39
	v_cvt_pk_bf16_f32 v38, v32, v33
	v_cvt_pk_bf16_f32 v39, v34, v35
	s_add_i32 s47, s17, 144
	v_add_u32_e32 v145, s47, v148
	v_and_b32_e32 v146, s46, v145
	v_lshlrev_b32_e32 v146, s30, v146
	v_lshrrev_b32_e32 v145, s19, v145
	v_add_u32_e32 v145, v145, v146
	v_lshrrev_b32_e32 v146, 5, v145
	v_and_b32_e32 v147, 31, v145
	v_lshlrev_b32_e32 v146, 12, v146
	v_lshl_or_b32 v146, v147, 4, v146
	v_add_u32_e32 v112, v146, v155
	global_store_dwordx4 v112, v[44:47], s[26:27]
	global_store_dwordx4 v112, v[36:39], s[26:27] offset:2048
	v_cvt_pk_bf16_f32 v28, v28, v29
	v_cvt_pk_bf16_f32 v29, v30, v31
	v_cvt_pk_bf16_f32 v30, v24, v25
	v_cvt_pk_bf16_f32 v31, v26, v27
	v_cvt_pk_bf16_f32 v20, v20, v21
	v_cvt_pk_bf16_f32 v21, v22, v23
	v_cvt_pk_bf16_f32 v22, v16, v17
	v_cvt_pk_bf16_f32 v23, v18, v19
	s_add_i32 s47, s17, 160
	v_add_u32_e32 v145, s47, v148
	v_and_b32_e32 v146, s46, v145
	v_lshlrev_b32_e32 v146, s30, v146
	v_lshrrev_b32_e32 v145, s19, v145
	v_add_u32_e32 v145, v145, v146
	v_lshrrev_b32_e32 v146, 5, v145
	v_and_b32_e32 v147, 31, v145
	v_lshlrev_b32_e32 v146, 12, v146
	v_lshl_or_b32 v146, v147, 4, v146
	v_add_u32_e32 v112, v146, v155
	global_store_dwordx4 v112, v[28:31], s[26:27]
	global_store_dwordx4 v112, v[20:23], s[26:27] offset:2048
	v_cvt_pk_bf16_f32 v12, v12, v13
	v_cvt_pk_bf16_f32 v13, v14, v15
	v_cvt_pk_bf16_f32 v14, v8, v9
	v_cvt_pk_bf16_f32 v15, v10, v11
	v_cvt_pk_bf16_f32 v4, v4, v5
	v_cvt_pk_bf16_f32 v5, v6, v7
	v_cvt_pk_bf16_f32 v6, v0, v1
	v_cvt_pk_bf16_f32 v7, v2, v3
	s_add_i32 s47, s17, 176
	v_add_u32_e32 v145, s47, v148
	v_and_b32_e32 v146, s46, v145
	v_lshlrev_b32_e32 v146, s30, v146
	v_lshrrev_b32_e32 v145, s19, v145
	v_add_u32_e32 v145, v145, v146
	v_lshrrev_b32_e32 v146, 5, v145
	v_and_b32_e32 v147, 31, v145
	v_lshlrev_b32_e32 v146, 12, v146
	v_lshl_or_b32 v146, v147, 4, v146
	v_add_u32_e32 v112, v146, v155
	global_store_dwordx4 v112, v[12:15], s[26:27]
	global_store_dwordx4 v112, v[4:7], s[26:27] offset:2048
